# up-proj GEMMs: unit order with the weight tile stationary for 4 consecutive units (row tile fastest) instead of the row tile stationary
# baseline (speedup 1.0000x reference)
;     __device__ bool next(int i, Unit& u) const {
;         const long L = (long)i * G + c; if (L >= nwg) return false;
;         int wgid = (int)L; { const int q = nwg / NXCD, r = nwg % NXCD, xcd = wgid % NXCD, off = wgid / NXCD; wgid = (xcd < r ? xcd * (q + 1) : r * (q + 1) + (xcd - r) * q) + off; }
;         const int nig = WGM * nN, gid = wgid / nig, fm = gid * WGM, gsz = (nM - fm) < WGM ? (nM - fm) : WGM;
;         u.pm = fm + ((wgid % nig) % gsz); u.pn = (wgid % nig) / gsz; return true;
;     }
.LBB0_763:
	s_add_i32 s34, s34, 1
	s_mul_i32 s0, s34, s37
	s_mul_hi_u32 s1, s34, s92
	s_add_i32 s1, s1, s0
	s_mul_i32 s0, s34, s92
	s_add_u32 s14, s0, s93
	s_addc_u32 s15, s1, s26
	v_cmp_gt_i64_e64 s[0:1], s[14:15], v[144:145]
	s_and_b64 vcc, exec, s[0:1]
	s_cbranch_vccnz .LBB0_769
	s_lshr_b32 s10, s14, 3
	s_bfe_u32 s11, s10, 0x20005
	s_bfe_u32 s13, s10, 0x20007
	s_and_b32 s10, s10, 31
	s_lshl_b32 s11, s11, 7
	s_lshl_b32 s13, s13, 5
	s_or_b32 s10, s10, s11
	s_or_b32 s10, s10, s13
	s_mov_b32 s13, 0
	s_sub_u32 s11, s10, 0x80
	s_cmp_ge_u32 s10, 0x80
	s_cselect_b32 s10, s11, s10
	s_addc_u32 s13, s13, 0
	s_sub_u32 s11, s10, 0x80
	s_cmp_ge_u32 s10, 0x80
	s_cselect_b32 s10, s11, s10
	s_addc_u32 s13, s13, 0
	s_sub_u32 s11, s10, 0x80
	s_cmp_ge_u32 s10, 0x80
	s_cselect_b32 s10, s11, s10
	s_addc_u32 s13, s13, 0
	s_and_b32 s12, s14, 7
	s_lshl_b32 s12, s12, 2
	s_add_i32 s12, s12, s13
	s_lshl_b32 s12, s12, 3
	s_and_b32 s13, s10, 7
	s_add_i32 s12, s12, s13
	s_lshr_b32 s10, s10, 3

;     __device__ bool next(int i, Unit& u) const {
;         const long L = (long)i * G + c; if (L >= nwg) return false;
;         int wgid = (int)L; { const int q = nwg / NXCD, r = nwg % NXCD, xcd = wgid % NXCD, off = wgid / NXCD; wgid = (xcd < r ? xcd * (q + 1) : r * (q + 1) + (xcd - r) * q) + off; }
;         const int nig = WGM * nN, gid = wgid / nig, fm = gid * WGM, gsz = (nM - fm) < WGM ? (nM - fm) : WGM;
;         u.pm = fm + ((wgid % nig) % gsz); u.pn = (wgid % nig) / gsz; return true;
;     }
.LBB0_1197:
	s_add_i32 s33, s33, 1
	s_mul_i32 s0, s33, s36
	s_mul_hi_u32 s1, s33, s92
	s_add_i32 s1, s1, s0
	s_mul_i32 s0, s33, s92
	s_add_u32 s14, s0, s93
	s_addc_u32 s15, s1, s9
	v_cmp_gt_i64_e64 s[0:1], s[14:15], v[144:145]
	s_and_b64 vcc, exec, s[0:1]
	s_cbranch_vccnz .LBB0_1203
	s_lshr_b32 s10, s14, 3
	s_bfe_u32 s11, s10, 0x20005
	s_bfe_u32 s13, s10, 0x20007
	s_and_b32 s10, s10, 31
	s_lshl_b32 s11, s11, 7
	s_lshl_b32 s13, s13, 5
	s_or_b32 s10, s10, s11
	s_or_b32 s10, s10, s13
	s_mov_b32 s13, 0
	s_sub_u32 s11, s10, 0x80
	s_cmp_ge_u32 s10, 0x80
	s_cselect_b32 s10, s11, s10
	s_addc_u32 s13, s13, 0
	s_sub_u32 s11, s10, 0x80
	s_cmp_ge_u32 s10, 0x80
	s_cselect_b32 s10, s11, s10
	s_addc_u32 s13, s13, 0
	s_sub_u32 s11, s10, 0x80
	s_cmp_ge_u32 s10, 0x80
	s_cselect_b32 s10, s11, s10
	s_addc_u32 s13, s13, 0
	s_and_b32 s12, s14, 7
	s_lshl_b32 s12, s12, 2
	s_add_i32 s12, s12, s13
	s_lshl_b32 s12, s12, 3
	s_and_b32 s13, s10, 7
	s_add_i32 s12, s12, s13
	s_lshr_b32 s10, s10, 3
